# plus attention stop-bound reduction via DPP instead of ds_bpermute, and P0 weight-transpose loops issuing all 32 loads of an item before the first wait
# speedup vs baseline: 1.0030x; 1.0030x over previous
.LBB0_30:
	v_lshl_add_u64 v[72:73], v[50:51], 0, s[4:5]
	v_lshl_add_u64 v[74:75], v[48:49], 0, s[4:5]
	v_lshl_add_u64 v[76:77], v[46:47], 0, s[4:5]
	v_lshl_add_u64 v[78:79], v[44:45], 0, s[4:5]
	v_lshl_add_u64 v[80:81], v[42:43], 0, s[4:5]
	v_lshl_add_u64 v[82:83], v[40:41], 0, s[4:5]
	v_lshl_add_u64 v[84:85], v[38:39], 0, s[4:5]
	v_lshl_add_u64 v[86:87], v[36:37], 0, s[4:5]
	global_load_dword v88, v[72:73], off nt
	global_load_dword v89, v[74:75], off nt
	global_load_dword v90, v[76:77], off nt
	global_load_dword v91, v[78:79], off nt
	global_load_dword v92, v[80:81], off nt
	global_load_dword v93, v[82:83], off nt
	global_load_dword v94, v[84:85], off nt
	global_load_dword v95, v[86:87], off nt
	s_add_u32 s4, s4, 0x2000
	s_addc_u32 s5, s5, 0
	v_lshl_add_u64 v[72:73], v[50:51], 0, s[4:5]
	v_lshl_add_u64 v[74:75], v[48:49], 0, s[4:5]
	v_lshl_add_u64 v[76:77], v[46:47], 0, s[4:5]
	v_lshl_add_u64 v[78:79], v[44:45], 0, s[4:5]
	v_lshl_add_u64 v[80:81], v[42:43], 0, s[4:5]
	v_lshl_add_u64 v[82:83], v[40:41], 0, s[4:5]
	v_lshl_add_u64 v[84:85], v[38:39], 0, s[4:5]
	v_lshl_add_u64 v[86:87], v[36:37], 0, s[4:5]
	global_load_dword v96, v[72:73], off nt
	global_load_dword v97, v[74:75], off nt
	global_load_dword v98, v[76:77], off nt
	global_load_dword v99, v[78:79], off nt
	global_load_dword v100, v[80:81], off nt
	global_load_dword v101, v[82:83], off nt
	global_load_dword v102, v[84:85], off nt
	global_load_dword v103, v[86:87], off nt
	s_add_u32 s4, s4, 0x2000
	s_addc_u32 s5, s5, 0
	v_lshl_add_u64 v[72:73], v[50:51], 0, s[4:5]
	v_lshl_add_u64 v[74:75], v[48:49], 0, s[4:5]
	v_lshl_add_u64 v[76:77], v[46:47], 0, s[4:5]
	v_lshl_add_u64 v[78:79], v[44:45], 0, s[4:5]
	v_lshl_add_u64 v[80:81], v[42:43], 0, s[4:5]
	v_lshl_add_u64 v[82:83], v[40:41], 0, s[4:5]
	v_lshl_add_u64 v[84:85], v[38:39], 0, s[4:5]
	v_lshl_add_u64 v[86:87], v[36:37], 0, s[4:5]
	global_load_dword v104, v[72:73], off nt
	global_load_dword v105, v[74:75], off nt
	global_load_dword v106, v[76:77], off nt
	global_load_dword v107, v[78:79], off nt
	global_load_dword v108, v[80:81], off nt
	global_load_dword v109, v[82:83], off nt
	global_load_dword v110, v[84:85], off nt
	global_load_dword v111, v[86:87], off nt
	s_add_u32 s4, s4, 0x2000
	s_addc_u32 s5, s5, 0
	v_lshl_add_u64 v[72:73], v[50:51], 0, s[4:5]
	v_lshl_add_u64 v[74:75], v[48:49], 0, s[4:5]
	v_lshl_add_u64 v[76:77], v[46:47], 0, s[4:5]
	v_lshl_add_u64 v[78:79], v[44:45], 0, s[4:5]
	v_lshl_add_u64 v[80:81], v[42:43], 0, s[4:5]
	v_lshl_add_u64 v[82:83], v[40:41], 0, s[4:5]
	v_lshl_add_u64 v[84:85], v[38:39], 0, s[4:5]
	v_lshl_add_u64 v[86:87], v[36:37], 0, s[4:5]
	global_load_dword v112, v[72:73], off nt
	global_load_dword v113, v[74:75], off nt
	global_load_dword v114, v[76:77], off nt
	global_load_dword v115, v[78:79], off nt
	global_load_dword v116, v[80:81], off nt
	global_load_dword v117, v[82:83], off nt
	global_load_dword v118, v[84:85], off nt
	global_load_dword v119, v[86:87], off nt
	s_add_u32 s4, s4, 0x2000
	s_addc_u32 s5, s5, 0
	v_add_u32_e32 v80, 0x400, v4
	s_waitcnt vmcnt(30)
	ds_write2_b32 v4, v88, v89 offset1:66
	s_waitcnt vmcnt(28)
	ds_write2_b32 v4, v90, v91 offset0:132 offset1:198
	s_waitcnt vmcnt(26)
	ds_write2_b32 v80, v92, v93 offset0:8 offset1:74
	s_waitcnt vmcnt(24)
	ds_write2_b32 v80, v94, v95 offset0:140 offset1:206
	v_add_u32_e32 v4, 0x840, v4
	v_add_u32_e32 v80, 0x400, v4
	s_waitcnt vmcnt(22)
	ds_write2_b32 v4, v96, v97 offset1:66
	s_waitcnt vmcnt(20)
	ds_write2_b32 v4, v98, v99 offset0:132 offset1:198
	s_waitcnt vmcnt(18)
	ds_write2_b32 v80, v100, v101 offset0:8 offset1:74
	s_waitcnt vmcnt(16)
	ds_write2_b32 v80, v102, v103 offset0:140 offset1:206
	v_add_u32_e32 v4, 0x840, v4
	v_add_u32_e32 v80, 0x400, v4
	s_waitcnt vmcnt(14)
	ds_write2_b32 v4, v104, v105 offset1:66
	s_waitcnt vmcnt(12)
	ds_write2_b32 v4, v106, v107 offset0:132 offset1:198
	s_waitcnt vmcnt(10)
	ds_write2_b32 v80, v108, v109 offset0:8 offset1:74
	s_waitcnt vmcnt(8)
	ds_write2_b32 v80, v110, v111 offset0:140 offset1:206
	v_add_u32_e32 v4, 0x840, v4
	v_add_u32_e32 v80, 0x400, v4
	s_waitcnt vmcnt(6)
	ds_write2_b32 v4, v112, v113 offset1:66
	s_waitcnt vmcnt(4)
	ds_write2_b32 v4, v114, v115 offset0:132 offset1:198
	s_waitcnt vmcnt(2)
	ds_write2_b32 v80, v116, v117 offset0:8 offset1:74
	s_waitcnt vmcnt(0)
	ds_write2_b32 v80, v118, v119 offset0:140 offset1:206
	v_add_u32_e32 v4, 0x840, v4
	s_add_i32 s2, s22, 0xffff2f80
	s_lshr_b32 s2, s2, 3
	s_add_i32 s2, s2, 16
	s_lshl_b64 s[4:5], s[2:3], 15
	s_add_u32 s2, s52, s4
	s_waitcnt lgkmcnt(0)
	s_addc_u32 s5, s53, s5
	s_lshl_b32 s4, s22, 5
	s_and_b32 s4, s4, 0x80
	ds_read2_b32 v[40:41], v53 offset0:33 offset1:41
	ds_read2_b32 v[42:43], v53 offset1:8
	ds_read2_b32 v[44:45], v53 offset0:66 offset1:74
	ds_read2_b32 v[46:47], v53 offset0:99 offset1:107
	ds_read2_b32 v[48:49], v53 offset0:132 offset1:140
	ds_read2_b32 v[50:51], v53 offset0:165 offset1:173
	ds_read2_b32 v[72:73], v53 offset0:198 offset1:206
	ds_read2_b32 v[74:75], v53 offset0:231 offset1:239
	s_add_u32 s4, s2, s4
	s_addc_u32 s5, s5, 0
	v_lshlrev_b32_e32 v4, 1, v2
	v_lshl_add_u64 v[76:77], s[4:5], 0, v[4:5]
	v_lshl_add_u64 v[78:79], v[76:77], 0, v[16:17]
	s_waitcnt lgkmcnt(6)
	v_cvt_pk_bf16_f32 v36, v42, v40
	s_waitcnt lgkmcnt(4)
	v_cvt_pk_bf16_f32 v37, v44, v46
	s_waitcnt lgkmcnt(2)
	v_cvt_pk_bf16_f32 v38, v48, v50
	s_waitcnt lgkmcnt(0)
	v_cvt_pk_bf16_f32 v39, v72, v74
	global_store_dwordx4 v[78:79], v[36:39], off
	s_mov_b64 s[4:5], 0
	s_nop 0
	v_cvt_pk_bf16_f32 v36, v43, v41
	v_cvt_pk_bf16_f32 v37, v45, v47
	v_cvt_pk_bf16_f32 v38, v49, v51
	v_cvt_pk_bf16_f32 v39, v73, v75
	ds_read2_b32 v[42:43], v53 offset0:16 offset1:24
	ds_read2_b32 v[44:45], v53 offset0:49 offset1:57
	ds_read2_b32 v[46:47], v53 offset0:82 offset1:90
	ds_read2_b32 v[48:49], v53 offset0:115 offset1:123
	ds_read2_b32 v[50:51], v53 offset0:148 offset1:156
	ds_read2_b32 v[72:73], v53 offset0:181 offset1:189
	ds_read2_b32 v[74:75], v53 offset0:214 offset1:222
	ds_read2_b32 v[78:79], v53 offset0:247 offset1:255
	v_lshl_add_u64 v[40:41], v[76:77], 0, v[18:19]
	global_store_dwordx4 v[40:41], v[36:39], off
	v_lshl_add_u64 v[40:41], v[76:77], 0, v[20:21]
	s_waitcnt lgkmcnt(6)
	v_cvt_pk_bf16_f32 v36, v42, v44
	s_waitcnt lgkmcnt(4)
	v_cvt_pk_bf16_f32 v37, v46, v48
	s_waitcnt lgkmcnt(2)
	v_cvt_pk_bf16_f32 v38, v50, v72
	s_waitcnt lgkmcnt(0)
	v_cvt_pk_bf16_f32 v39, v74, v78
	global_store_dwordx4 v[40:41], v[36:39], off
	v_lshl_add_u64 v[40:41], v[76:77], 0, v[22:23]
	s_nop 0
	v_cvt_pk_bf16_f32 v36, v43, v45
	v_cvt_pk_bf16_f32 v37, v47, v49
	v_cvt_pk_bf16_f32 v38, v51, v73
	v_cvt_pk_bf16_f32 v39, v75, v79
	global_store_dwordx4 v[40:41], v[36:39], off
	s_waitcnt lgkmcnt(0)

.LBB0_34:
	v_lshl_add_u64 v[64:65], v[50:51], 0, s[4:5]
	v_lshl_add_u64 v[66:67], v[48:49], 0, s[4:5]
	v_lshl_add_u64 v[68:69], v[46:47], 0, s[4:5]
	v_lshl_add_u64 v[70:71], v[44:45], 0, s[4:5]
	v_lshl_add_u64 v[72:73], v[42:43], 0, s[4:5]
	v_lshl_add_u64 v[74:75], v[40:41], 0, s[4:5]
	v_lshl_add_u64 v[76:77], v[38:39], 0, s[4:5]
	v_lshl_add_u64 v[78:79], v[36:37], 0, s[4:5]
	global_load_dword v88, v[64:65], off nt
	global_load_dword v89, v[66:67], off nt
	global_load_dword v90, v[68:69], off nt
	global_load_dword v91, v[70:71], off nt
	global_load_dword v92, v[72:73], off nt
	global_load_dword v93, v[74:75], off nt
	global_load_dword v94, v[76:77], off nt
	global_load_dword v95, v[78:79], off nt
	s_add_u32 s4, s4, 0x2000
	s_addc_u32 s5, s5, 0
	v_lshl_add_u64 v[64:65], v[50:51], 0, s[4:5]
	v_lshl_add_u64 v[66:67], v[48:49], 0, s[4:5]
	v_lshl_add_u64 v[68:69], v[46:47], 0, s[4:5]
	v_lshl_add_u64 v[70:71], v[44:45], 0, s[4:5]
	v_lshl_add_u64 v[72:73], v[42:43], 0, s[4:5]
	v_lshl_add_u64 v[74:75], v[40:41], 0, s[4:5]
	v_lshl_add_u64 v[76:77], v[38:39], 0, s[4:5]
	v_lshl_add_u64 v[78:79], v[36:37], 0, s[4:5]
	global_load_dword v96, v[64:65], off nt
	global_load_dword v97, v[66:67], off nt
	global_load_dword v98, v[68:69], off nt
	global_load_dword v99, v[70:71], off nt
	global_load_dword v100, v[72:73], off nt
	global_load_dword v101, v[74:75], off nt
	global_load_dword v102, v[76:77], off nt
	global_load_dword v103, v[78:79], off nt
	s_add_u32 s4, s4, 0x2000
	s_addc_u32 s5, s5, 0
	v_lshl_add_u64 v[64:65], v[50:51], 0, s[4:5]
	v_lshl_add_u64 v[66:67], v[48:49], 0, s[4:5]
	v_lshl_add_u64 v[68:69], v[46:47], 0, s[4:5]
	v_lshl_add_u64 v[70:71], v[44:45], 0, s[4:5]
	v_lshl_add_u64 v[72:73], v[42:43], 0, s[4:5]
	v_lshl_add_u64 v[74:75], v[40:41], 0, s[4:5]
	v_lshl_add_u64 v[76:77], v[38:39], 0, s[4:5]
	v_lshl_add_u64 v[78:79], v[36:37], 0, s[4:5]
	global_load_dword v104, v[64:65], off nt
	global_load_dword v105, v[66:67], off nt
	global_load_dword v106, v[68:69], off nt
	global_load_dword v107, v[70:71], off nt
	global_load_dword v108, v[72:73], off nt
	global_load_dword v109, v[74:75], off nt
	global_load_dword v110, v[76:77], off nt
	global_load_dword v111, v[78:79], off nt
	s_add_u32 s4, s4, 0x2000
	s_addc_u32 s5, s5, 0
	v_lshl_add_u64 v[64:65], v[50:51], 0, s[4:5]
	v_lshl_add_u64 v[66:67], v[48:49], 0, s[4:5]
	v_lshl_add_u64 v[68:69], v[46:47], 0, s[4:5]
	v_lshl_add_u64 v[70:71], v[44:45], 0, s[4:5]
	v_lshl_add_u64 v[72:73], v[42:43], 0, s[4:5]
	v_lshl_add_u64 v[74:75], v[40:41], 0, s[4:5]
	v_lshl_add_u64 v[76:77], v[38:39], 0, s[4:5]
	v_lshl_add_u64 v[78:79], v[36:37], 0, s[4:5]
	global_load_dword v112, v[64:65], off nt
	global_load_dword v113, v[66:67], off nt
	global_load_dword v114, v[68:69], off nt
	global_load_dword v115, v[70:71], off nt
	global_load_dword v116, v[72:73], off nt
	global_load_dword v117, v[74:75], off nt
	global_load_dword v118, v[76:77], off nt
	global_load_dword v119, v[78:79], off nt
	s_add_u32 s4, s4, 0x2000
	s_addc_u32 s5, s5, 0
	v_add_u32_e32 v72, 0x400, v4
	s_waitcnt vmcnt(30)
	ds_write2_b32 v4, v88, v89 offset1:66
	s_waitcnt vmcnt(28)
	ds_write2_b32 v4, v90, v91 offset0:132 offset1:198
	s_waitcnt vmcnt(26)
	ds_write2_b32 v72, v92, v93 offset0:8 offset1:74
	s_waitcnt vmcnt(24)
	ds_write2_b32 v72, v94, v95 offset0:140 offset1:206
	v_add_u32_e32 v4, 0x840, v4
	v_add_u32_e32 v72, 0x400, v4
	s_waitcnt vmcnt(22)
	ds_write2_b32 v4, v96, v97 offset1:66
	s_waitcnt vmcnt(20)
	ds_write2_b32 v4, v98, v99 offset0:132 offset1:198
	s_waitcnt vmcnt(18)
	ds_write2_b32 v72, v100, v101 offset0:8 offset1:74
	s_waitcnt vmcnt(16)
	ds_write2_b32 v72, v102, v103 offset0:140 offset1:206
	v_add_u32_e32 v4, 0x840, v4
	v_add_u32_e32 v72, 0x400, v4
	s_waitcnt vmcnt(14)
	ds_write2_b32 v4, v104, v105 offset1:66
	s_waitcnt vmcnt(12)
	ds_write2_b32 v4, v106, v107 offset0:132 offset1:198
	s_waitcnt vmcnt(10)
	ds_write2_b32 v72, v108, v109 offset0:8 offset1:74
	s_waitcnt vmcnt(8)
	ds_write2_b32 v72, v110, v111 offset0:140 offset1:206
	v_add_u32_e32 v4, 0x840, v4
	v_add_u32_e32 v72, 0x400, v4
	s_waitcnt vmcnt(6)
	ds_write2_b32 v4, v112, v113 offset1:66
	s_waitcnt vmcnt(4)
	ds_write2_b32 v4, v114, v115 offset0:132 offset1:198
	s_waitcnt vmcnt(2)
	ds_write2_b32 v72, v116, v117 offset0:8 offset1:74
	s_waitcnt vmcnt(0)
	ds_write2_b32 v72, v118, v119 offset0:140 offset1:206
	v_add_u32_e32 v4, 0x840, v4
	s_add_i32 s2, s22, 0xffff3000
	s_lshr_b32 s2, s2, 3
	s_lshl_b64 s[4:5], s[2:3], 15
	s_add_u32 s2, s52, s4
	s_waitcnt lgkmcnt(0)
	s_addc_u32 s5, s53, s5
	s_lshl_b32 s4, s22, 5
	s_and_b32 s4, s4, 0x80
	ds_read2_b32 v[40:41], v53 offset0:33 offset1:41
	ds_read2_b32 v[42:43], v53 offset1:8
	ds_read2_b32 v[44:45], v53 offset0:66 offset1:74
	ds_read2_b32 v[46:47], v53 offset0:99 offset1:107
	ds_read2_b32 v[48:49], v53 offset0:132 offset1:140
	ds_read2_b32 v[50:51], v53 offset0:165 offset1:173
	ds_read2_b32 v[64:65], v53 offset0:198 offset1:206
	ds_read2_b32 v[66:67], v53 offset0:231 offset1:239
	s_add_u32 s4, s2, s4
	s_addc_u32 s5, s5, 0
	v_lshlrev_b32_e32 v4, 1, v2
	v_lshl_add_u64 v[68:69], s[4:5], 0, v[4:5]
	v_lshl_add_u64 v[70:71], v[68:69], 0, v[16:17]
	s_waitcnt lgkmcnt(6)
	v_cvt_pk_bf16_f32 v36, v42, v40
	s_waitcnt lgkmcnt(4)
	v_cvt_pk_bf16_f32 v37, v44, v46
	s_waitcnt lgkmcnt(2)
	v_cvt_pk_bf16_f32 v38, v48, v50
	s_waitcnt lgkmcnt(0)
	v_cvt_pk_bf16_f32 v39, v64, v66
	global_store_dwordx4 v[70:71], v[36:39], off
	s_nop 1
	v_cvt_pk_bf16_f32 v36, v43, v41
	v_cvt_pk_bf16_f32 v37, v45, v47
	v_cvt_pk_bf16_f32 v38, v49, v51
	v_cvt_pk_bf16_f32 v39, v65, v67
	ds_read2_b32 v[42:43], v53 offset0:16 offset1:24
	ds_read2_b32 v[44:45], v53 offset0:49 offset1:57
	ds_read2_b32 v[46:47], v53 offset0:82 offset1:90
	ds_read2_b32 v[48:49], v53 offset0:115 offset1:123
	ds_read2_b32 v[50:51], v53 offset0:148 offset1:156
	ds_read2_b32 v[64:65], v53 offset0:181 offset1:189
	ds_read2_b32 v[66:67], v53 offset0:214 offset1:222
	ds_read2_b32 v[70:71], v53 offset0:247 offset1:255
	v_lshl_add_u64 v[40:41], v[68:69], 0, v[18:19]
	global_store_dwordx4 v[40:41], v[36:39], off
	v_lshl_add_u64 v[40:41], v[68:69], 0, v[20:21]
	s_waitcnt lgkmcnt(6)
	v_cvt_pk_bf16_f32 v36, v42, v44
	s_waitcnt lgkmcnt(4)
	v_cvt_pk_bf16_f32 v37, v46, v48
	s_waitcnt lgkmcnt(2)
	v_cvt_pk_bf16_f32 v38, v50, v64
	s_waitcnt lgkmcnt(0)
	v_cvt_pk_bf16_f32 v39, v66, v70
	global_store_dwordx4 v[40:41], v[36:39], off
	v_lshl_add_u64 v[40:41], v[68:69], 0, v[22:23]
	s_nop 0
	v_cvt_pk_bf16_f32 v36, v43, v45
	v_cvt_pk_bf16_f32 v37, v47, v49
	v_cvt_pk_bf16_f32 v38, v51, v65
	v_cvt_pk_bf16_f32 v39, v67, v71
	global_store_dwordx4 v[40:41], v[36:39], off
	s_waitcnt lgkmcnt(0)

.LBB0_39:
	v_lshl_add_u64 v[64:65], v[50:51], 0, s[4:5]
	v_lshl_add_u64 v[66:67], v[48:49], 0, s[4:5]
	v_lshl_add_u64 v[68:69], v[46:47], 0, s[4:5]
	v_lshl_add_u64 v[70:71], v[44:45], 0, s[4:5]
	v_lshl_add_u64 v[72:73], v[42:43], 0, s[4:5]
	v_lshl_add_u64 v[74:75], v[40:41], 0, s[4:5]
	v_lshl_add_u64 v[76:77], v[38:39], 0, s[4:5]
	v_lshl_add_u64 v[78:79], v[36:37], 0, s[4:5]
	global_load_dword v88, v[64:65], off nt
	global_load_dword v89, v[66:67], off nt
	global_load_dword v90, v[68:69], off nt
	global_load_dword v91, v[70:71], off nt
	global_load_dword v92, v[72:73], off nt
	global_load_dword v93, v[74:75], off nt
	global_load_dword v94, v[76:77], off nt
	global_load_dword v95, v[78:79], off nt
	s_add_u32 s4, s4, 0x40000
	s_addc_u32 s5, s5, 0
	v_lshl_add_u64 v[64:65], v[50:51], 0, s[4:5]
	v_lshl_add_u64 v[66:67], v[48:49], 0, s[4:5]
	v_lshl_add_u64 v[68:69], v[46:47], 0, s[4:5]
	v_lshl_add_u64 v[70:71], v[44:45], 0, s[4:5]
	v_lshl_add_u64 v[72:73], v[42:43], 0, s[4:5]
	v_lshl_add_u64 v[74:75], v[40:41], 0, s[4:5]
	v_lshl_add_u64 v[76:77], v[38:39], 0, s[4:5]
	v_lshl_add_u64 v[78:79], v[36:37], 0, s[4:5]
	global_load_dword v96, v[64:65], off nt
	global_load_dword v97, v[66:67], off nt
	global_load_dword v98, v[68:69], off nt
	global_load_dword v99, v[70:71], off nt
	global_load_dword v100, v[72:73], off nt
	global_load_dword v101, v[74:75], off nt
	global_load_dword v102, v[76:77], off nt
	global_load_dword v103, v[78:79], off nt
	s_add_u32 s4, s4, 0x40000
	s_addc_u32 s5, s5, 0
	v_lshl_add_u64 v[64:65], v[50:51], 0, s[4:5]
	v_lshl_add_u64 v[66:67], v[48:49], 0, s[4:5]
	v_lshl_add_u64 v[68:69], v[46:47], 0, s[4:5]
	v_lshl_add_u64 v[70:71], v[44:45], 0, s[4:5]
	v_lshl_add_u64 v[72:73], v[42:43], 0, s[4:5]
	v_lshl_add_u64 v[74:75], v[40:41], 0, s[4:5]
	v_lshl_add_u64 v[76:77], v[38:39], 0, s[4:5]
	v_lshl_add_u64 v[78:79], v[36:37], 0, s[4:5]
	global_load_dword v104, v[64:65], off nt
	global_load_dword v105, v[66:67], off nt
	global_load_dword v106, v[68:69], off nt
	global_load_dword v107, v[70:71], off nt
	global_load_dword v108, v[72:73], off nt
	global_load_dword v109, v[74:75], off nt
	global_load_dword v110, v[76:77], off nt
	global_load_dword v111, v[78:79], off nt
	s_add_u32 s4, s4, 0x40000
	s_addc_u32 s5, s5, 0
	v_lshl_add_u64 v[64:65], v[50:51], 0, s[4:5]
	v_lshl_add_u64 v[66:67], v[48:49], 0, s[4:5]
	v_lshl_add_u64 v[68:69], v[46:47], 0, s[4:5]
	v_lshl_add_u64 v[70:71], v[44:45], 0, s[4:5]
	v_lshl_add_u64 v[72:73], v[42:43], 0, s[4:5]
	v_lshl_add_u64 v[74:75], v[40:41], 0, s[4:5]
	v_lshl_add_u64 v[76:77], v[38:39], 0, s[4:5]
	v_lshl_add_u64 v[78:79], v[36:37], 0, s[4:5]
	global_load_dword v112, v[64:65], off nt
	global_load_dword v113, v[66:67], off nt
	global_load_dword v114, v[68:69], off nt
	global_load_dword v115, v[70:71], off nt
	global_load_dword v116, v[72:73], off nt
	global_load_dword v117, v[74:75], off nt
	global_load_dword v118, v[76:77], off nt
	global_load_dword v119, v[78:79], off nt
	s_add_u32 s4, s4, 0x40000
	s_addc_u32 s5, s5, 0
	v_add_u32_e32 v72, 0x400, v4
	s_waitcnt vmcnt(30)
	ds_write2_b32 v4, v88, v89 offset1:66
	s_waitcnt vmcnt(28)
	ds_write2_b32 v4, v90, v91 offset0:132 offset1:198
	s_waitcnt vmcnt(26)
	ds_write2_b32 v72, v92, v93 offset0:8 offset1:74
	s_waitcnt vmcnt(24)
	ds_write2_b32 v72, v94, v95 offset0:140 offset1:206
	v_add_u32_e32 v4, 0x840, v4
	v_add_u32_e32 v72, 0x400, v4
	s_waitcnt vmcnt(22)
	ds_write2_b32 v4, v96, v97 offset1:66
	s_waitcnt vmcnt(20)
	ds_write2_b32 v4, v98, v99 offset0:132 offset1:198
	s_waitcnt vmcnt(18)
	ds_write2_b32 v72, v100, v101 offset0:8 offset1:74
	s_waitcnt vmcnt(16)
	ds_write2_b32 v72, v102, v103 offset0:140 offset1:206
	v_add_u32_e32 v4, 0x840, v4
	v_add_u32_e32 v72, 0x400, v4
	s_waitcnt vmcnt(14)
	ds_write2_b32 v4, v104, v105 offset1:66
	s_waitcnt vmcnt(12)
	ds_write2_b32 v4, v106, v107 offset0:132 offset1:198
	s_waitcnt vmcnt(10)
	ds_write2_b32 v72, v108, v109 offset0:8 offset1:74
	s_waitcnt vmcnt(8)
	ds_write2_b32 v72, v110, v111 offset0:140 offset1:206
	v_add_u32_e32 v4, 0x840, v4
	v_add_u32_e32 v72, 0x400, v4
	s_waitcnt vmcnt(6)
	ds_write2_b32 v4, v112, v113 offset1:66
	s_waitcnt vmcnt(4)
	ds_write2_b32 v4, v114, v115 offset0:132 offset1:198
	s_waitcnt vmcnt(2)
	ds_write2_b32 v72, v116, v117 offset0:8 offset1:74
	s_waitcnt vmcnt(0)
	ds_write2_b32 v72, v118, v119 offset0:140 offset1:206
	v_add_u32_e32 v4, 0x840, v4
	s_waitcnt lgkmcnt(0)
	s_lshl_b32 s2, s22, 5
	ds_read2_b32 v[40:41], v53 offset0:33 offset1:41
	ds_read2_b32 v[42:43], v53 offset1:8
	ds_read2_b32 v[44:45], v53 offset0:66 offset1:74
	ds_read2_b32 v[46:47], v53 offset0:99 offset1:107
	ds_read2_b32 v[48:49], v53 offset0:132 offset1:140
	ds_read2_b32 v[50:51], v53 offset0:165 offset1:173
	ds_read2_b32 v[64:65], v53 offset0:198 offset1:206
	ds_read2_b32 v[66:67], v53 offset0:231 offset1:239
	s_and_b32 s4, s2, 0xfe0
	s_add_i32 s2, s22, 0x5000
	s_and_b32 s2, s2, 0xff80
	v_or_b32_e32 v4, s4, v52
	v_lshl_add_u64 v[68:69], v[6:7], 0, s[2:3]
	v_lshlrev_b32_e32 v4, 13, v4
	v_lshl_add_u64 v[70:71], v[68:69], 0, v[4:5]
	s_waitcnt lgkmcnt(6)
	v_cvt_pk_bf16_f32 v36, v42, v40
	s_waitcnt lgkmcnt(4)
	v_cvt_pk_bf16_f32 v37, v44, v46
	s_waitcnt lgkmcnt(2)
	v_cvt_pk_bf16_f32 v38, v48, v50
	s_waitcnt lgkmcnt(0)
	v_cvt_pk_bf16_f32 v39, v64, v66
	global_store_dwordx4 v[70:71], v[36:39], off
	v_or_b32_e32 v4, s4, v54
	v_lshlrev_b32_e32 v4, 13, v4
	v_cvt_pk_bf16_f32 v36, v43, v41
	v_cvt_pk_bf16_f32 v37, v45, v47
	v_cvt_pk_bf16_f32 v38, v49, v51
	v_cvt_pk_bf16_f32 v39, v65, v67
	ds_read2_b32 v[42:43], v53 offset0:16 offset1:24
	ds_read2_b32 v[44:45], v53 offset0:49 offset1:57
	ds_read2_b32 v[46:47], v53 offset0:82 offset1:90
	ds_read2_b32 v[48:49], v53 offset0:115 offset1:123
	ds_read2_b32 v[50:51], v53 offset0:148 offset1:156
	ds_read2_b32 v[64:65], v53 offset0:181 offset1:189
	ds_read2_b32 v[66:67], v53 offset0:214 offset1:222
	ds_read2_b32 v[70:71], v53 offset0:247 offset1:255
	v_lshl_add_u64 v[40:41], v[68:69], 0, v[4:5]
	v_or_b32_e32 v4, s4, v55
	v_lshlrev_b32_e32 v4, 13, v4
	global_store_dwordx4 v[40:41], v[36:39], off
	v_lshl_add_u64 v[40:41], v[68:69], 0, v[4:5]
	v_or_b32_e32 v4, s4, v56
	v_lshlrev_b32_e32 v4, 13, v4
	s_waitcnt lgkmcnt(6)
	v_cvt_pk_bf16_f32 v36, v42, v44
	s_waitcnt lgkmcnt(4)
	v_cvt_pk_bf16_f32 v37, v46, v48
	s_waitcnt lgkmcnt(2)
	v_cvt_pk_bf16_f32 v38, v50, v64
	s_waitcnt lgkmcnt(0)
	v_cvt_pk_bf16_f32 v39, v66, v70
	global_store_dwordx4 v[40:41], v[36:39], off
	v_lshl_add_u64 v[40:41], v[68:69], 0, v[4:5]
	s_nop 0
	v_cvt_pk_bf16_f32 v36, v43, v45
	v_cvt_pk_bf16_f32 v37, v47, v49
	v_cvt_pk_bf16_f32 v38, v51, v65
	v_cvt_pk_bf16_f32 v39, v67, v71
	global_store_dwordx4 v[40:41], v[36:39], off
	s_waitcnt lgkmcnt(0)

.LBB0_44:
	v_lshl_add_u64 v[64:65], v[50:51], 0, s[4:5]
	v_lshl_add_u64 v[66:67], v[48:49], 0, s[4:5]
	v_lshl_add_u64 v[68:69], v[46:47], 0, s[4:5]
	v_lshl_add_u64 v[70:71], v[44:45], 0, s[4:5]
	v_lshl_add_u64 v[72:73], v[42:43], 0, s[4:5]
	v_lshl_add_u64 v[74:75], v[40:41], 0, s[4:5]
	v_lshl_add_u64 v[76:77], v[38:39], 0, s[4:5]
	v_lshl_add_u64 v[78:79], v[36:37], 0, s[4:5]
	global_load_dword v88, v[64:65], off nt
	global_load_dword v89, v[66:67], off nt
	global_load_dword v90, v[68:69], off nt
	global_load_dword v91, v[70:71], off nt
	global_load_dword v92, v[72:73], off nt
	global_load_dword v93, v[74:75], off nt
	global_load_dword v94, v[76:77], off nt
	global_load_dword v95, v[78:79], off nt
	s_add_u32 s4, s4, 0x40000
	s_addc_u32 s5, s5, 0
	v_lshl_add_u64 v[64:65], v[50:51], 0, s[4:5]
	v_lshl_add_u64 v[66:67], v[48:49], 0, s[4:5]
	v_lshl_add_u64 v[68:69], v[46:47], 0, s[4:5]
	v_lshl_add_u64 v[70:71], v[44:45], 0, s[4:5]
	v_lshl_add_u64 v[72:73], v[42:43], 0, s[4:5]
	v_lshl_add_u64 v[74:75], v[40:41], 0, s[4:5]
	v_lshl_add_u64 v[76:77], v[38:39], 0, s[4:5]
	v_lshl_add_u64 v[78:79], v[36:37], 0, s[4:5]
	global_load_dword v96, v[64:65], off nt
	global_load_dword v97, v[66:67], off nt
	global_load_dword v98, v[68:69], off nt
	global_load_dword v99, v[70:71], off nt
	global_load_dword v100, v[72:73], off nt
	global_load_dword v101, v[74:75], off nt
	global_load_dword v102, v[76:77], off nt
	global_load_dword v103, v[78:79], off nt
	s_add_u32 s4, s4, 0x40000
	s_addc_u32 s5, s5, 0
	v_lshl_add_u64 v[64:65], v[50:51], 0, s[4:5]
	v_lshl_add_u64 v[66:67], v[48:49], 0, s[4:5]
	v_lshl_add_u64 v[68:69], v[46:47], 0, s[4:5]
	v_lshl_add_u64 v[70:71], v[44:45], 0, s[4:5]
	v_lshl_add_u64 v[72:73], v[42:43], 0, s[4:5]
	v_lshl_add_u64 v[74:75], v[40:41], 0, s[4:5]
	v_lshl_add_u64 v[76:77], v[38:39], 0, s[4:5]
	v_lshl_add_u64 v[78:79], v[36:37], 0, s[4:5]
	global_load_dword v104, v[64:65], off nt
	global_load_dword v105, v[66:67], off nt
	global_load_dword v106, v[68:69], off nt
	global_load_dword v107, v[70:71], off nt
	global_load_dword v108, v[72:73], off nt
	global_load_dword v109, v[74:75], off nt
	global_load_dword v110, v[76:77], off nt
	global_load_dword v111, v[78:79], off nt
	s_add_u32 s4, s4, 0x40000
	s_addc_u32 s5, s5, 0
	v_lshl_add_u64 v[64:65], v[50:51], 0, s[4:5]
	v_lshl_add_u64 v[66:67], v[48:49], 0, s[4:5]
	v_lshl_add_u64 v[68:69], v[46:47], 0, s[4:5]
	v_lshl_add_u64 v[70:71], v[44:45], 0, s[4:5]
	v_lshl_add_u64 v[72:73], v[42:43], 0, s[4:5]
	v_lshl_add_u64 v[74:75], v[40:41], 0, s[4:5]
	v_lshl_add_u64 v[76:77], v[38:39], 0, s[4:5]
	v_lshl_add_u64 v[78:79], v[36:37], 0, s[4:5]
	global_load_dword v112, v[64:65], off nt
	global_load_dword v113, v[66:67], off nt
	global_load_dword v114, v[68:69], off nt
	global_load_dword v115, v[70:71], off nt
	global_load_dword v116, v[72:73], off nt
	global_load_dword v117, v[74:75], off nt
	global_load_dword v118, v[76:77], off nt
	global_load_dword v119, v[78:79], off nt
	s_add_u32 s4, s4, 0x40000
	s_addc_u32 s5, s5, 0
	v_add_u32_e32 v72, 0x400, v4
	s_waitcnt vmcnt(30)
	ds_write2_b32 v4, v88, v89 offset1:66
	s_waitcnt vmcnt(28)
	ds_write2_b32 v4, v90, v91 offset0:132 offset1:198
	s_waitcnt vmcnt(26)
	ds_write2_b32 v72, v92, v93 offset0:8 offset1:74
	s_waitcnt vmcnt(24)
	ds_write2_b32 v72, v94, v95 offset0:140 offset1:206
	v_add_u32_e32 v4, 0x840, v4
	v_add_u32_e32 v72, 0x400, v4
	s_waitcnt vmcnt(22)
	ds_write2_b32 v4, v96, v97 offset1:66
	s_waitcnt vmcnt(20)
	ds_write2_b32 v4, v98, v99 offset0:132 offset1:198
	s_waitcnt vmcnt(18)
	ds_write2_b32 v72, v100, v101 offset0:8 offset1:74
	s_waitcnt vmcnt(16)
	ds_write2_b32 v72, v102, v103 offset0:140 offset1:206
	v_add_u32_e32 v4, 0x840, v4
	v_add_u32_e32 v72, 0x400, v4
	s_waitcnt vmcnt(14)
	ds_write2_b32 v4, v104, v105 offset1:66
	s_waitcnt vmcnt(12)
	ds_write2_b32 v4, v106, v107 offset0:132 offset1:198
	s_waitcnt vmcnt(10)
	ds_write2_b32 v72, v108, v109 offset0:8 offset1:74
	s_waitcnt vmcnt(8)
	ds_write2_b32 v72, v110, v111 offset0:140 offset1:206
	v_add_u32_e32 v4, 0x840, v4
	v_add_u32_e32 v72, 0x400, v4
	s_waitcnt vmcnt(6)
	ds_write2_b32 v4, v112, v113 offset1:66
	s_waitcnt vmcnt(4)
	ds_write2_b32 v4, v114, v115 offset0:132 offset1:198
	s_waitcnt vmcnt(2)
	ds_write2_b32 v72, v116, v117 offset0:8 offset1:74
	s_waitcnt vmcnt(0)
	ds_write2_b32 v72, v118, v119 offset0:140 offset1:206
	v_add_u32_e32 v4, 0x840, v4
	s_waitcnt lgkmcnt(0)
	s_lshl_b32 s2, s22, 5
	ds_read2_b32 v[40:41], v53 offset0:33 offset1:41
	ds_read2_b32 v[42:43], v53 offset1:8
	ds_read2_b32 v[44:45], v53 offset0:66 offset1:74
	ds_read2_b32 v[46:47], v53 offset0:99 offset1:107
	ds_read2_b32 v[48:49], v53 offset0:132 offset1:140
	ds_read2_b32 v[50:51], v53 offset0:165 offset1:173
	ds_read2_b32 v[64:65], v53 offset0:198 offset1:206
	ds_read2_b32 v[66:67], v53 offset0:231 offset1:239
	s_and_b32 s4, s2, 0xfe0
	s_add_i32 s2, s22, 0x6000
	s_and_b32 s2, s2, 0xff80
	v_or_b32_e32 v4, s4, v52
	v_lshl_add_u64 v[68:69], v[8:9], 0, s[2:3]
	v_lshlrev_b32_e32 v4, 12, v4
	v_lshl_add_u64 v[70:71], v[68:69], 0, v[4:5]
	s_waitcnt lgkmcnt(6)
	v_cvt_pk_bf16_f32 v36, v42, v40
	s_waitcnt lgkmcnt(4)
	v_cvt_pk_bf16_f32 v37, v44, v46
	s_waitcnt lgkmcnt(2)
	v_cvt_pk_bf16_f32 v38, v48, v50
	s_waitcnt lgkmcnt(0)
	v_cvt_pk_bf16_f32 v39, v64, v66
	global_store_dwordx4 v[70:71], v[36:39], off
	v_or_b32_e32 v4, s4, v54
	v_lshlrev_b32_e32 v4, 12, v4
	v_cvt_pk_bf16_f32 v36, v43, v41
	v_cvt_pk_bf16_f32 v37, v45, v47
	v_cvt_pk_bf16_f32 v38, v49, v51
	v_cvt_pk_bf16_f32 v39, v65, v67
	ds_read2_b32 v[42:43], v53 offset0:16 offset1:24
	ds_read2_b32 v[44:45], v53 offset0:49 offset1:57
	ds_read2_b32 v[46:47], v53 offset0:82 offset1:90
	ds_read2_b32 v[48:49], v53 offset0:115 offset1:123
	ds_read2_b32 v[50:51], v53 offset0:148 offset1:156
	ds_read2_b32 v[64:65], v53 offset0:181 offset1:189
	ds_read2_b32 v[66:67], v53 offset0:214 offset1:222
	ds_read2_b32 v[70:71], v53 offset0:247 offset1:255
	v_lshl_add_u64 v[40:41], v[68:69], 0, v[4:5]
	v_or_b32_e32 v4, s4, v55
	v_lshlrev_b32_e32 v4, 12, v4
	global_store_dwordx4 v[40:41], v[36:39], off
	v_lshl_add_u64 v[40:41], v[68:69], 0, v[4:5]
	v_or_b32_e32 v4, s4, v56
	v_lshlrev_b32_e32 v4, 12, v4
	s_waitcnt lgkmcnt(6)
	v_cvt_pk_bf16_f32 v36, v42, v44
	s_waitcnt lgkmcnt(4)
	v_cvt_pk_bf16_f32 v37, v46, v48
	s_waitcnt lgkmcnt(2)
	v_cvt_pk_bf16_f32 v38, v50, v64
	s_waitcnt lgkmcnt(0)
	v_cvt_pk_bf16_f32 v39, v66, v70
	global_store_dwordx4 v[40:41], v[36:39], off
	v_lshl_add_u64 v[40:41], v[68:69], 0, v[4:5]
	s_nop 0
	v_cvt_pk_bf16_f32 v36, v43, v45
	v_cvt_pk_bf16_f32 v37, v47, v49
	v_cvt_pk_bf16_f32 v38, v51, v65
	v_cvt_pk_bf16_f32 v39, v67, v71
	global_store_dwordx4 v[40:41], v[36:39], off
	s_waitcnt lgkmcnt(0)

.LBB0_49:
	v_lshl_add_u64 v[64:65], v[50:51], 0, s[4:5]
	v_lshl_add_u64 v[66:67], v[48:49], 0, s[4:5]
	v_lshl_add_u64 v[68:69], v[46:47], 0, s[4:5]
	v_lshl_add_u64 v[70:71], v[44:45], 0, s[4:5]
	v_lshl_add_u64 v[72:73], v[42:43], 0, s[4:5]
	v_lshl_add_u64 v[74:75], v[40:41], 0, s[4:5]
	v_lshl_add_u64 v[76:77], v[38:39], 0, s[4:5]
	v_lshl_add_u64 v[78:79], v[36:37], 0, s[4:5]
	global_load_dword v88, v[64:65], off nt
	global_load_dword v89, v[66:67], off nt
	global_load_dword v90, v[68:69], off nt
	global_load_dword v91, v[70:71], off nt
	global_load_dword v92, v[72:73], off nt
	global_load_dword v93, v[74:75], off nt
	global_load_dword v94, v[76:77], off nt
	global_load_dword v95, v[78:79], off nt
	s_add_u32 s4, s4, 0x40000
	s_addc_u32 s5, s5, 0
	v_lshl_add_u64 v[64:65], v[50:51], 0, s[4:5]
	v_lshl_add_u64 v[66:67], v[48:49], 0, s[4:5]
	v_lshl_add_u64 v[68:69], v[46:47], 0, s[4:5]
	v_lshl_add_u64 v[70:71], v[44:45], 0, s[4:5]
	v_lshl_add_u64 v[72:73], v[42:43], 0, s[4:5]
	v_lshl_add_u64 v[74:75], v[40:41], 0, s[4:5]
	v_lshl_add_u64 v[76:77], v[38:39], 0, s[4:5]
	v_lshl_add_u64 v[78:79], v[36:37], 0, s[4:5]
	global_load_dword v96, v[64:65], off nt
	global_load_dword v97, v[66:67], off nt
	global_load_dword v98, v[68:69], off nt
	global_load_dword v99, v[70:71], off nt
	global_load_dword v100, v[72:73], off nt
	global_load_dword v101, v[74:75], off nt
	global_load_dword v102, v[76:77], off nt
	global_load_dword v103, v[78:79], off nt
	s_add_u32 s4, s4, 0x40000
	s_addc_u32 s5, s5, 0
	v_lshl_add_u64 v[64:65], v[50:51], 0, s[4:5]
	v_lshl_add_u64 v[66:67], v[48:49], 0, s[4:5]
	v_lshl_add_u64 v[68:69], v[46:47], 0, s[4:5]
	v_lshl_add_u64 v[70:71], v[44:45], 0, s[4:5]
	v_lshl_add_u64 v[72:73], v[42:43], 0, s[4:5]
	v_lshl_add_u64 v[74:75], v[40:41], 0, s[4:5]
	v_lshl_add_u64 v[76:77], v[38:39], 0, s[4:5]
	v_lshl_add_u64 v[78:79], v[36:37], 0, s[4:5]
	global_load_dword v104, v[64:65], off nt
	global_load_dword v105, v[66:67], off nt
	global_load_dword v106, v[68:69], off nt
	global_load_dword v107, v[70:71], off nt
	global_load_dword v108, v[72:73], off nt
	global_load_dword v109, v[74:75], off nt
	global_load_dword v110, v[76:77], off nt
	global_load_dword v111, v[78:79], off nt
	s_add_u32 s4, s4, 0x40000
	s_addc_u32 s5, s5, 0
	v_lshl_add_u64 v[64:65], v[50:51], 0, s[4:5]
	v_lshl_add_u64 v[66:67], v[48:49], 0, s[4:5]
	v_lshl_add_u64 v[68:69], v[46:47], 0, s[4:5]
	v_lshl_add_u64 v[70:71], v[44:45], 0, s[4:5]
	v_lshl_add_u64 v[72:73], v[42:43], 0, s[4:5]
	v_lshl_add_u64 v[74:75], v[40:41], 0, s[4:5]
	v_lshl_add_u64 v[76:77], v[38:39], 0, s[4:5]
	v_lshl_add_u64 v[78:79], v[36:37], 0, s[4:5]
	global_load_dword v112, v[64:65], off nt
	global_load_dword v113, v[66:67], off nt
	global_load_dword v114, v[68:69], off nt
	global_load_dword v115, v[70:71], off nt
	global_load_dword v116, v[72:73], off nt
	global_load_dword v117, v[74:75], off nt
	global_load_dword v118, v[76:77], off nt
	global_load_dword v119, v[78:79], off nt
	s_add_u32 s4, s4, 0x40000
	s_addc_u32 s5, s5, 0
	v_add_u32_e32 v72, 0x400, v4
	s_waitcnt vmcnt(31)
	v_mul_f32_e32 v88, 0x42800000, v88
	s_waitcnt vmcnt(30)
	v_mul_f32_e32 v89, 0x42800000, v89
	s_waitcnt vmcnt(29)
	v_mul_f32_e32 v90, 0x42800000, v90
	s_waitcnt vmcnt(28)
	v_mul_f32_e32 v91, 0x42800000, v91
	s_waitcnt vmcnt(27)
	v_mul_f32_e32 v92, 0x42800000, v92
	s_waitcnt vmcnt(26)
	v_mul_f32_e32 v93, 0x42800000, v93
	s_waitcnt vmcnt(25)
	v_mul_f32_e32 v94, 0x42800000, v94
	s_waitcnt vmcnt(24)
	v_mul_f32_e32 v95, 0x42800000, v95
	ds_write2_b32 v4, v88, v89 offset1:66
	ds_write2_b32 v4, v90, v91 offset0:132 offset1:198
	ds_write2_b32 v72, v92, v93 offset0:8 offset1:74
	ds_write2_b32 v72, v94, v95 offset0:140 offset1:206
	v_add_u32_e32 v4, 0x840, v4
	v_add_u32_e32 v72, 0x400, v4
	s_waitcnt vmcnt(23)
	v_mul_f32_e32 v96, 0x42800000, v96
	s_waitcnt vmcnt(22)
	v_mul_f32_e32 v97, 0x42800000, v97
	s_waitcnt vmcnt(21)
	v_mul_f32_e32 v98, 0x42800000, v98
	s_waitcnt vmcnt(20)
	v_mul_f32_e32 v99, 0x42800000, v99
	s_waitcnt vmcnt(19)
	v_mul_f32_e32 v100, 0x42800000, v100
	s_waitcnt vmcnt(18)
	v_mul_f32_e32 v101, 0x42800000, v101
	s_waitcnt vmcnt(17)
	v_mul_f32_e32 v102, 0x42800000, v102
	s_waitcnt vmcnt(16)
	v_mul_f32_e32 v103, 0x42800000, v103
	ds_write2_b32 v4, v96, v97 offset1:66
	ds_write2_b32 v4, v98, v99 offset0:132 offset1:198
	ds_write2_b32 v72, v100, v101 offset0:8 offset1:74
	ds_write2_b32 v72, v102, v103 offset0:140 offset1:206
	v_add_u32_e32 v4, 0x840, v4
	v_add_u32_e32 v72, 0x400, v4
	s_waitcnt vmcnt(15)
	v_mul_f32_e32 v104, 0x42800000, v104
	s_waitcnt vmcnt(14)
	v_mul_f32_e32 v105, 0x42800000, v105
	s_waitcnt vmcnt(13)
	v_mul_f32_e32 v106, 0x42800000, v106
	s_waitcnt vmcnt(12)
	v_mul_f32_e32 v107, 0x42800000, v107
	s_waitcnt vmcnt(11)
	v_mul_f32_e32 v108, 0x42800000, v108
	s_waitcnt vmcnt(10)
	v_mul_f32_e32 v109, 0x42800000, v109
	s_waitcnt vmcnt(9)
	v_mul_f32_e32 v110, 0x42800000, v110
	s_waitcnt vmcnt(8)
	v_mul_f32_e32 v111, 0x42800000, v111
	ds_write2_b32 v4, v104, v105 offset1:66
	ds_write2_b32 v4, v106, v107 offset0:132 offset1:198
	ds_write2_b32 v72, v108, v109 offset0:8 offset1:74
	ds_write2_b32 v72, v110, v111 offset0:140 offset1:206
	v_add_u32_e32 v4, 0x840, v4
	v_add_u32_e32 v72, 0x400, v4
	s_waitcnt vmcnt(7)
	v_mul_f32_e32 v112, 0x42800000, v112
	s_waitcnt vmcnt(6)
	v_mul_f32_e32 v113, 0x42800000, v113
	s_waitcnt vmcnt(5)
	v_mul_f32_e32 v114, 0x42800000, v114
	s_waitcnt vmcnt(4)
	v_mul_f32_e32 v115, 0x42800000, v115
	s_waitcnt vmcnt(3)
	v_mul_f32_e32 v116, 0x42800000, v116
	s_waitcnt vmcnt(2)
	v_mul_f32_e32 v117, 0x42800000, v117
	s_waitcnt vmcnt(1)
	v_mul_f32_e32 v118, 0x42800000, v118
	s_waitcnt vmcnt(0)
	v_mul_f32_e32 v119, 0x42800000, v119
	ds_write2_b32 v4, v112, v113 offset1:66
	ds_write2_b32 v4, v114, v115 offset0:132 offset1:198
	ds_write2_b32 v72, v116, v117 offset0:8 offset1:74
	ds_write2_b32 v72, v118, v119 offset0:140 offset1:206
	v_add_u32_e32 v4, 0x840, v4
	s_waitcnt lgkmcnt(0)
	ds_read2_b32 v[36:37], v53 offset0:33 offset1:41
	ds_read2_b32 v[38:39], v53 offset0:66 offset1:74
	ds_read2_b32 v[40:41], v53 offset1:8
	ds_read2_b32 v[42:43], v53 offset0:99 offset1:107
	ds_read2_b32 v[46:47], v53 offset0:132 offset1:140
	ds_read2_b32 v[48:49], v53 offset0:165 offset1:173
	v_mov_b32_e32 v44, v5
	ds_read2_b32 v[50:51], v53 offset0:198 offset1:206
	ds_read2_b32 v[64:65], v53 offset0:231 offset1:239
	v_mov_b32_e32 v45, v5
	s_waitcnt lgkmcnt(5)
	v_cvt_pk_fp8_f32 v44, v40, v36
	s_waitcnt lgkmcnt(2)
	v_cvt_pk_fp8_f32 v45, v46, v48
	s_add_i32 s2, s22, 0xffff7000
	s_lshl_b32 s4, s22, 5
	v_mov_b32_e32 v36, v5
	s_lshr_b32 s2, s2, 1
	s_and_b32 s4, s4, 0xfe0
	v_cvt_pk_fp8_f32 v44, v38, v42 op_sel:[0,0,1]
	s_waitcnt lgkmcnt(0)
	v_cvt_pk_fp8_f32 v45, v50, v64 op_sel:[0,0,1]
	v_cvt_pk_fp8_f32 v36, v41, v37
	v_mov_b32_e32 v37, v5
	s_and_b32 s2, s2, 0x7fffffc0
	v_or_b32_e32 v4, s4, v52
	v_cvt_pk_fp8_f32 v37, v47, v49
	v_lshl_add_u64 v[66:67], v[10:11], 0, s[2:3]
	v_lshlrev_b32_e32 v4, 11, v4
	v_lshl_add_u64 v[40:41], v[66:67], 0, v[4:5]
	global_store_dwordx2 v[40:41], v[44:45], off
	v_cvt_pk_fp8_f32 v36, v39, v43 op_sel:[0,0,1]
	v_cvt_pk_fp8_f32 v37, v51, v65 op_sel:[0,0,1]
	ds_read2_b32 v[38:39], v53 offset0:49 offset1:57
	ds_read2_b32 v[40:41], v53 offset0:82 offset1:90
	ds_read2_b32 v[42:43], v53 offset0:16 offset1:24
	ds_read2_b32 v[44:45], v53 offset0:115 offset1:123
	ds_read2_b32 v[48:49], v53 offset0:148 offset1:156
	ds_read2_b32 v[50:51], v53 offset0:181 offset1:189
	v_or_b32_e32 v4, s4, v54
	v_lshlrev_b32_e32 v4, 11, v4
	v_mov_b32_e32 v46, v5
	ds_read2_b32 v[64:65], v53 offset0:214 offset1:222
	ds_read2_b32 v[68:69], v53 offset0:247 offset1:255
	v_mov_b32_e32 v47, v5
	v_lshl_add_u64 v[70:71], v[66:67], 0, v[4:5]
	s_waitcnt lgkmcnt(5)
	v_cvt_pk_fp8_f32 v46, v42, v38
	s_waitcnt lgkmcnt(2)
	v_cvt_pk_fp8_f32 v47, v48, v50
	global_store_dwordx2 v[70:71], v[36:37], off
	v_mov_b32_e32 v36, v5
	v_mov_b32_e32 v37, v5
	v_cvt_pk_fp8_f32 v36, v43, v39
	v_cvt_pk_fp8_f32 v37, v49, v51
	v_cvt_pk_fp8_f32 v46, v40, v44 op_sel:[0,0,1]
	s_waitcnt lgkmcnt(0)
	v_cvt_pk_fp8_f32 v47, v64, v68 op_sel:[0,0,1]
	v_or_b32_e32 v4, s4, v55
	v_lshlrev_b32_e32 v4, 11, v4
	v_cvt_pk_fp8_f32 v36, v41, v45 op_sel:[0,0,1]
	v_cvt_pk_fp8_f32 v37, v65, v69 op_sel:[0,0,1]
	v_lshl_add_u64 v[38:39], v[66:67], 0, v[4:5]
	v_or_b32_e32 v4, s4, v56
	v_lshlrev_b32_e32 v4, 11, v4
	global_store_dwordx2 v[38:39], v[46:47], off
	v_lshl_add_u64 v[38:39], v[66:67], 0, v[4:5]
	global_store_dwordx2 v[38:39], v[36:37], off
	s_waitcnt lgkmcnt(0)

.LBB0_55:
	v_lshl_add_u64 v[72:73], v[50:51], 0, s[10:11]
	v_lshl_add_u64 v[74:75], v[48:49], 0, s[10:11]
	v_lshl_add_u64 v[76:77], v[46:47], 0, s[10:11]
	v_lshl_add_u64 v[78:79], v[44:45], 0, s[10:11]
	v_lshl_add_u64 v[80:81], v[42:43], 0, s[10:11]
	v_lshl_add_u64 v[82:83], v[40:41], 0, s[10:11]
	v_lshl_add_u64 v[84:85], v[38:39], 0, s[10:11]
	v_lshl_add_u64 v[86:87], v[36:37], 0, s[10:11]
	global_load_dword v88, v[72:73], off nt
	global_load_dword v89, v[74:75], off nt
	global_load_dword v90, v[76:77], off nt
	global_load_dword v91, v[78:79], off nt
	global_load_dword v92, v[80:81], off nt
	global_load_dword v93, v[82:83], off nt
	global_load_dword v94, v[84:85], off nt
	global_load_dword v95, v[86:87], off nt
	s_add_u32 s10, s10, 0x120000
	s_addc_u32 s11, s11, 0
	v_lshl_add_u64 v[72:73], v[50:51], 0, s[10:11]
	v_lshl_add_u64 v[74:75], v[48:49], 0, s[10:11]
	v_lshl_add_u64 v[76:77], v[46:47], 0, s[10:11]
	v_lshl_add_u64 v[78:79], v[44:45], 0, s[10:11]
	v_lshl_add_u64 v[80:81], v[42:43], 0, s[10:11]
	v_lshl_add_u64 v[82:83], v[40:41], 0, s[10:11]
	v_lshl_add_u64 v[84:85], v[38:39], 0, s[10:11]
	v_lshl_add_u64 v[86:87], v[36:37], 0, s[10:11]
	global_load_dword v96, v[72:73], off nt
	global_load_dword v97, v[74:75], off nt
	global_load_dword v98, v[76:77], off nt
	global_load_dword v99, v[78:79], off nt
	global_load_dword v100, v[80:81], off nt
	global_load_dword v101, v[82:83], off nt
	global_load_dword v102, v[84:85], off nt
	global_load_dword v103, v[86:87], off nt
	s_add_u32 s10, s10, 0x120000
	s_addc_u32 s11, s11, 0
	v_lshl_add_u64 v[72:73], v[50:51], 0, s[10:11]
	v_lshl_add_u64 v[74:75], v[48:49], 0, s[10:11]
	v_lshl_add_u64 v[76:77], v[46:47], 0, s[10:11]
	v_lshl_add_u64 v[78:79], v[44:45], 0, s[10:11]
	v_lshl_add_u64 v[80:81], v[42:43], 0, s[10:11]
	v_lshl_add_u64 v[82:83], v[40:41], 0, s[10:11]
	v_lshl_add_u64 v[84:85], v[38:39], 0, s[10:11]
	v_lshl_add_u64 v[86:87], v[36:37], 0, s[10:11]
	global_load_dword v104, v[72:73], off nt
	global_load_dword v105, v[74:75], off nt
	global_load_dword v106, v[76:77], off nt
	global_load_dword v107, v[78:79], off nt
	global_load_dword v108, v[80:81], off nt
	global_load_dword v109, v[82:83], off nt
	global_load_dword v110, v[84:85], off nt
	global_load_dword v111, v[86:87], off nt
	s_add_u32 s10, s10, 0x120000
	s_addc_u32 s11, s11, 0
	v_lshl_add_u64 v[72:73], v[50:51], 0, s[10:11]
	v_lshl_add_u64 v[74:75], v[48:49], 0, s[10:11]
	v_lshl_add_u64 v[76:77], v[46:47], 0, s[10:11]
	v_lshl_add_u64 v[78:79], v[44:45], 0, s[10:11]
	v_lshl_add_u64 v[80:81], v[42:43], 0, s[10:11]
	v_lshl_add_u64 v[82:83], v[40:41], 0, s[10:11]
	v_lshl_add_u64 v[84:85], v[38:39], 0, s[10:11]
	v_lshl_add_u64 v[86:87], v[36:37], 0, s[10:11]
	global_load_dword v112, v[72:73], off nt
	global_load_dword v113, v[74:75], off nt
	global_load_dword v114, v[76:77], off nt
	global_load_dword v115, v[78:79], off nt
	global_load_dword v116, v[80:81], off nt
	global_load_dword v117, v[82:83], off nt
	global_load_dword v118, v[84:85], off nt
	global_load_dword v119, v[86:87], off nt
	s_add_u32 s10, s10, 0x120000
	s_addc_u32 s11, s11, 0
	v_add_u32_e32 v80, 0x400, v71
	s_waitcnt vmcnt(30)
	ds_write2_b32 v71, v88, v89 offset1:66
	s_waitcnt vmcnt(28)
	ds_write2_b32 v71, v90, v91 offset0:132 offset1:198
	s_waitcnt vmcnt(26)
	ds_write2_b32 v80, v92, v93 offset0:8 offset1:74
	s_waitcnt vmcnt(24)
	ds_write2_b32 v80, v94, v95 offset0:140 offset1:206
	v_add_u32_e32 v71, 0x840, v71
	v_add_u32_e32 v80, 0x400, v71
	s_waitcnt vmcnt(22)
	ds_write2_b32 v71, v96, v97 offset1:66
	s_waitcnt vmcnt(20)
	ds_write2_b32 v71, v98, v99 offset0:132 offset1:198
	s_waitcnt vmcnt(18)
	ds_write2_b32 v80, v100, v101 offset0:8 offset1:74
	s_waitcnt vmcnt(16)
	ds_write2_b32 v80, v102, v103 offset0:140 offset1:206
	v_add_u32_e32 v71, 0x840, v71
	v_add_u32_e32 v80, 0x400, v71
	s_waitcnt vmcnt(14)
	ds_write2_b32 v71, v104, v105 offset1:66
	s_waitcnt vmcnt(12)
	ds_write2_b32 v71, v106, v107 offset0:132 offset1:198
	s_waitcnt vmcnt(10)
	ds_write2_b32 v80, v108, v109 offset0:8 offset1:74
	s_waitcnt vmcnt(8)
	ds_write2_b32 v80, v110, v111 offset0:140 offset1:206
	v_add_u32_e32 v71, 0x840, v71
	v_add_u32_e32 v80, 0x400, v71
	s_waitcnt vmcnt(6)
	ds_write2_b32 v71, v112, v113 offset1:66
	s_waitcnt vmcnt(4)
	ds_write2_b32 v71, v114, v115 offset0:132 offset1:198
	s_waitcnt vmcnt(2)
	ds_write2_b32 v80, v116, v117 offset0:8 offset1:74
	s_waitcnt vmcnt(0)
	ds_write2_b32 v80, v118, v119 offset0:140 offset1:206
	v_add_u32_e32 v71, 0x840, v71
	s_waitcnt lgkmcnt(0)
	ds_read2_b32 v[40:41], v53 offset0:33 offset1:41
	ds_read2_b32 v[42:43], v53 offset1:8
	ds_read2_b32 v[44:45], v53 offset0:66 offset1:74
	ds_read2_b32 v[46:47], v53 offset0:99 offset1:107
	ds_read2_b32 v[48:49], v53 offset0:132 offset1:140
	ds_read2_b32 v[50:51], v53 offset0:165 offset1:173
	ds_read2_b32 v[72:73], v53 offset0:198 offset1:206
	ds_read2_b32 v[74:75], v53 offset0:231 offset1:239
	v_or_b32_e32 v78, s8, v52
	s_ashr_i32 s5, s4, 31
	v_ashrrev_i32_e32 v79, 31, v78
	v_lshl_add_u64 v[76:77], s[4:5], 1, v[12:13]
	v_lshlrev_b64 v[78:79], 13, v[78:79]
	s_waitcnt lgkmcnt(6)
	v_cvt_pk_bf16_f32 v36, v42, v40
	v_lshl_add_u64 v[78:79], v[76:77], 0, v[78:79]
	v_or_b32_e32 v40, s8, v54
	s_waitcnt lgkmcnt(4)
	v_cvt_pk_bf16_f32 v37, v44, v46
	s_waitcnt lgkmcnt(2)
	v_cvt_pk_bf16_f32 v38, v48, v50
	s_waitcnt lgkmcnt(0)
	v_cvt_pk_bf16_f32 v39, v72, v74
	global_store_dwordx4 v[78:79], v[36:39], off
	s_mov_b64 s[10:11], 0
	s_nop 0
	v_cvt_pk_bf16_f32 v36, v43, v41
	v_ashrrev_i32_e32 v41, 31, v40
	v_lshlrev_b64 v[40:41], 13, v[40:41]
	v_cvt_pk_bf16_f32 v37, v45, v47
	v_cvt_pk_bf16_f32 v38, v49, v51
	v_cvt_pk_bf16_f32 v39, v73, v75
	v_lshl_add_u64 v[40:41], v[76:77], 0, v[40:41]
	ds_read2_b32 v[42:43], v53 offset0:16 offset1:24
	ds_read2_b32 v[44:45], v53 offset0:49 offset1:57
	ds_read2_b32 v[46:47], v53 offset0:82 offset1:90
	ds_read2_b32 v[48:49], v53 offset0:115 offset1:123
	ds_read2_b32 v[50:51], v53 offset0:148 offset1:156
	ds_read2_b32 v[72:73], v53 offset0:181 offset1:189
	ds_read2_b32 v[74:75], v53 offset0:214 offset1:222
	ds_read2_b32 v[78:79], v53 offset0:247 offset1:255
	global_store_dwordx4 v[40:41], v[36:39], off
	v_or_b32_e32 v40, s8, v55
	v_ashrrev_i32_e32 v41, 31, v40
	v_lshlrev_b64 v[40:41], 13, v[40:41]
	v_lshl_add_u64 v[40:41], v[76:77], 0, v[40:41]
	s_waitcnt lgkmcnt(6)
	v_cvt_pk_bf16_f32 v36, v42, v44
	s_waitcnt lgkmcnt(4)
	v_cvt_pk_bf16_f32 v37, v46, v48
	s_waitcnt lgkmcnt(2)
	v_cvt_pk_bf16_f32 v38, v50, v72
	s_waitcnt lgkmcnt(0)
	v_cvt_pk_bf16_f32 v39, v74, v78
	global_store_dwordx4 v[40:41], v[36:39], off
	v_or_b32_e32 v40, s8, v56
	v_ashrrev_i32_e32 v41, 31, v40
	v_lshlrev_b64 v[40:41], 13, v[40:41]
	v_lshl_add_u64 v[40:41], v[76:77], 0, v[40:41]
	v_cvt_pk_bf16_f32 v36, v43, v45
	v_cvt_pk_bf16_f32 v37, v47, v49
	v_cvt_pk_bf16_f32 v38, v51, v73
	v_cvt_pk_bf16_f32 v39, v75, v79
	global_store_dwordx4 v[40:41], v[36:39], off
	s_waitcnt lgkmcnt(0)

.LBB0_59:
	v_lshl_add_u64 v[64:65], v[50:51], 0, s[8:9]
	v_lshl_add_u64 v[66:67], v[48:49], 0, s[8:9]
	v_lshl_add_u64 v[68:69], v[46:47], 0, s[8:9]
	v_lshl_add_u64 v[70:71], v[44:45], 0, s[8:9]
	v_lshl_add_u64 v[72:73], v[42:43], 0, s[8:9]
	v_lshl_add_u64 v[74:75], v[40:41], 0, s[8:9]
	v_lshl_add_u64 v[76:77], v[38:39], 0, s[8:9]
	v_lshl_add_u64 v[78:79], v[36:37], 0, s[8:9]
	global_load_dword v88, v[64:65], off nt
	global_load_dword v89, v[66:67], off nt
	global_load_dword v90, v[68:69], off nt
	global_load_dword v91, v[70:71], off nt
	global_load_dword v92, v[72:73], off nt
	global_load_dword v93, v[74:75], off nt
	global_load_dword v94, v[76:77], off nt
	global_load_dword v95, v[78:79], off nt
	s_add_u32 s8, s8, 0x120000
	s_addc_u32 s9, s9, 0
	v_lshl_add_u64 v[64:65], v[50:51], 0, s[8:9]
	v_lshl_add_u64 v[66:67], v[48:49], 0, s[8:9]
	v_lshl_add_u64 v[68:69], v[46:47], 0, s[8:9]
	v_lshl_add_u64 v[70:71], v[44:45], 0, s[8:9]
	v_lshl_add_u64 v[72:73], v[42:43], 0, s[8:9]
	v_lshl_add_u64 v[74:75], v[40:41], 0, s[8:9]
	v_lshl_add_u64 v[76:77], v[38:39], 0, s[8:9]
	v_lshl_add_u64 v[78:79], v[36:37], 0, s[8:9]
	global_load_dword v96, v[64:65], off nt
	global_load_dword v97, v[66:67], off nt
	global_load_dword v98, v[68:69], off nt
	global_load_dword v99, v[70:71], off nt
	global_load_dword v100, v[72:73], off nt
	global_load_dword v101, v[74:75], off nt
	global_load_dword v102, v[76:77], off nt
	global_load_dword v103, v[78:79], off nt
	s_add_u32 s8, s8, 0x120000
	s_addc_u32 s9, s9, 0
	v_lshl_add_u64 v[64:65], v[50:51], 0, s[8:9]
	v_lshl_add_u64 v[66:67], v[48:49], 0, s[8:9]
	v_lshl_add_u64 v[68:69], v[46:47], 0, s[8:9]
	v_lshl_add_u64 v[70:71], v[44:45], 0, s[8:9]
	v_lshl_add_u64 v[72:73], v[42:43], 0, s[8:9]
	v_lshl_add_u64 v[74:75], v[40:41], 0, s[8:9]
	v_lshl_add_u64 v[76:77], v[38:39], 0, s[8:9]
	v_lshl_add_u64 v[78:79], v[36:37], 0, s[8:9]
	global_load_dword v104, v[64:65], off nt
	global_load_dword v105, v[66:67], off nt
	global_load_dword v106, v[68:69], off nt
	global_load_dword v107, v[70:71], off nt
	global_load_dword v108, v[72:73], off nt
	global_load_dword v109, v[74:75], off nt
	global_load_dword v110, v[76:77], off nt
	global_load_dword v111, v[78:79], off nt
	s_add_u32 s8, s8, 0x120000
	s_addc_u32 s9, s9, 0
	v_lshl_add_u64 v[64:65], v[50:51], 0, s[8:9]
	v_lshl_add_u64 v[66:67], v[48:49], 0, s[8:9]
	v_lshl_add_u64 v[68:69], v[46:47], 0, s[8:9]
	v_lshl_add_u64 v[70:71], v[44:45], 0, s[8:9]
	v_lshl_add_u64 v[72:73], v[42:43], 0, s[8:9]
	v_lshl_add_u64 v[74:75], v[40:41], 0, s[8:9]
	v_lshl_add_u64 v[76:77], v[38:39], 0, s[8:9]
	v_lshl_add_u64 v[78:79], v[36:37], 0, s[8:9]
	global_load_dword v112, v[64:65], off nt
	global_load_dword v113, v[66:67], off nt
	global_load_dword v114, v[68:69], off nt
	global_load_dword v115, v[70:71], off nt
	global_load_dword v116, v[72:73], off nt
	global_load_dword v117, v[74:75], off nt
	global_load_dword v118, v[76:77], off nt
	global_load_dword v119, v[78:79], off nt
	s_add_u32 s8, s8, 0x120000
	s_addc_u32 s9, s9, 0
	v_add_u32_e32 v72, 0x400, v4
	s_waitcnt vmcnt(31)
	v_mul_f32_e32 v88, 0x43000000, v88
	s_waitcnt vmcnt(30)
	v_mul_f32_e32 v89, 0x43000000, v89
	s_waitcnt vmcnt(29)
	v_mul_f32_e32 v90, 0x43000000, v90
	s_waitcnt vmcnt(28)
	v_mul_f32_e32 v91, 0x43000000, v91
	s_waitcnt vmcnt(27)
	v_mul_f32_e32 v92, 0x43000000, v92
	s_waitcnt vmcnt(26)
	v_mul_f32_e32 v93, 0x43000000, v93
	s_waitcnt vmcnt(25)
	v_mul_f32_e32 v94, 0x43000000, v94
	s_waitcnt vmcnt(24)
	v_mul_f32_e32 v95, 0x43000000, v95
	ds_write2_b32 v4, v88, v89 offset1:66
	ds_write2_b32 v4, v90, v91 offset0:132 offset1:198
	ds_write2_b32 v72, v92, v93 offset0:8 offset1:74
	ds_write2_b32 v72, v94, v95 offset0:140 offset1:206
	v_add_u32_e32 v4, 0x840, v4
	v_add_u32_e32 v72, 0x400, v4
	s_waitcnt vmcnt(23)
	v_mul_f32_e32 v96, 0x43000000, v96
	s_waitcnt vmcnt(22)
	v_mul_f32_e32 v97, 0x43000000, v97
	s_waitcnt vmcnt(21)
	v_mul_f32_e32 v98, 0x43000000, v98
	s_waitcnt vmcnt(20)
	v_mul_f32_e32 v99, 0x43000000, v99
	s_waitcnt vmcnt(19)
	v_mul_f32_e32 v100, 0x43000000, v100
	s_waitcnt vmcnt(18)
	v_mul_f32_e32 v101, 0x43000000, v101
	s_waitcnt vmcnt(17)
	v_mul_f32_e32 v102, 0x43000000, v102
	s_waitcnt vmcnt(16)
	v_mul_f32_e32 v103, 0x43000000, v103
	ds_write2_b32 v4, v96, v97 offset1:66
	ds_write2_b32 v4, v98, v99 offset0:132 offset1:198
	ds_write2_b32 v72, v100, v101 offset0:8 offset1:74
	ds_write2_b32 v72, v102, v103 offset0:140 offset1:206
	v_add_u32_e32 v4, 0x840, v4
	v_add_u32_e32 v72, 0x400, v4
	s_waitcnt vmcnt(15)
	v_mul_f32_e32 v104, 0x43000000, v104
	s_waitcnt vmcnt(14)
	v_mul_f32_e32 v105, 0x43000000, v105
	s_waitcnt vmcnt(13)
	v_mul_f32_e32 v106, 0x43000000, v106
	s_waitcnt vmcnt(12)
	v_mul_f32_e32 v107, 0x43000000, v107
	s_waitcnt vmcnt(11)
	v_mul_f32_e32 v108, 0x43000000, v108
	s_waitcnt vmcnt(10)
	v_mul_f32_e32 v109, 0x43000000, v109
	s_waitcnt vmcnt(9)
	v_mul_f32_e32 v110, 0x43000000, v110
	s_waitcnt vmcnt(8)
	v_mul_f32_e32 v111, 0x43000000, v111
	ds_write2_b32 v4, v104, v105 offset1:66
	ds_write2_b32 v4, v106, v107 offset0:132 offset1:198
	ds_write2_b32 v72, v108, v109 offset0:8 offset1:74
	ds_write2_b32 v72, v110, v111 offset0:140 offset1:206
	v_add_u32_e32 v4, 0x840, v4
	v_add_u32_e32 v72, 0x400, v4
	s_waitcnt vmcnt(7)
	v_mul_f32_e32 v112, 0x43000000, v112
	s_waitcnt vmcnt(6)
	v_mul_f32_e32 v113, 0x43000000, v113
	s_waitcnt vmcnt(5)
	v_mul_f32_e32 v114, 0x43000000, v114
	s_waitcnt vmcnt(4)
	v_mul_f32_e32 v115, 0x43000000, v115
	s_waitcnt vmcnt(3)
	v_mul_f32_e32 v116, 0x43000000, v116
	s_waitcnt vmcnt(2)
	v_mul_f32_e32 v117, 0x43000000, v117
	s_waitcnt vmcnt(1)
	v_mul_f32_e32 v118, 0x43000000, v118
	s_waitcnt vmcnt(0)
	v_mul_f32_e32 v119, 0x43000000, v119
	ds_write2_b32 v4, v112, v113 offset1:66
	ds_write2_b32 v4, v114, v115 offset0:132 offset1:198
	ds_write2_b32 v72, v116, v117 offset0:8 offset1:74
	ds_write2_b32 v72, v118, v119 offset0:140 offset1:206
	v_add_u32_e32 v4, 0x840, v4
	s_waitcnt lgkmcnt(0)
	ds_read2_b32 v[36:37], v53 offset0:33 offset1:41
	ds_read2_b32 v[38:39], v53 offset0:66 offset1:74
	ds_read2_b32 v[40:41], v53 offset1:8
	ds_read2_b32 v[42:43], v53 offset0:99 offset1:107
	ds_read2_b32 v[46:47], v53 offset0:132 offset1:140
	ds_read2_b32 v[48:49], v53 offset0:165 offset1:173
	v_mov_b32_e32 v44, 0
	ds_read2_b32 v[50:51], v53 offset0:198 offset1:206
	ds_read2_b32 v[64:65], v53 offset0:231 offset1:239
	v_mov_b32_e32 v45, 0
	s_waitcnt lgkmcnt(5)
	v_cvt_pk_fp8_f32 v44, v40, v36
	s_waitcnt lgkmcnt(2)
	v_cvt_pk_fp8_f32 v45, v46, v48
	v_mov_b32_e32 v36, v5
	v_cvt_pk_fp8_f32 v36, v41, v37
	v_cvt_pk_fp8_f32 v44, v38, v42 op_sel:[0,0,1]
	s_waitcnt lgkmcnt(0)
	v_cvt_pk_fp8_f32 v45, v50, v64 op_sel:[0,0,1]
	v_mov_b32_e32 v37, v5
	s_ashr_i32 s5, s4, 31
	v_cvt_pk_fp8_f32 v37, v47, v49
	v_lshl_add_u64 v[66:67], v[14:15], 0, s[4:5]
	v_add_lshl_u32 v4, s2, v52, 12
	v_lshl_add_u64 v[40:41], v[66:67], 0, v[4:5]
	global_store_dwordx2 v[40:41], v[44:45], off
	v_cvt_pk_fp8_f32 v36, v39, v43 op_sel:[0,0,1]
	v_cvt_pk_fp8_f32 v37, v51, v65 op_sel:[0,0,1]
	ds_read2_b32 v[38:39], v53 offset0:49 offset1:57
	ds_read2_b32 v[40:41], v53 offset0:82 offset1:90
	ds_read2_b32 v[42:43], v53 offset0:16 offset1:24
	ds_read2_b32 v[44:45], v53 offset0:115 offset1:123
	ds_read2_b32 v[48:49], v53 offset0:148 offset1:156
	ds_read2_b32 v[50:51], v53 offset0:181 offset1:189
	v_add_lshl_u32 v4, s2, v54, 12
	v_mov_b32_e32 v46, v5
	ds_read2_b32 v[64:65], v53 offset0:214 offset1:222
	ds_read2_b32 v[68:69], v53 offset0:247 offset1:255
	v_mov_b32_e32 v47, v5
	v_lshl_add_u64 v[70:71], v[66:67], 0, v[4:5]
	s_waitcnt lgkmcnt(5)
	v_cvt_pk_fp8_f32 v46, v42, v38
	s_waitcnt lgkmcnt(2)
	v_cvt_pk_fp8_f32 v47, v48, v50
	global_store_dwordx2 v[70:71], v[36:37], off
	v_mov_b32_e32 v36, v5
	v_mov_b32_e32 v37, v5
	v_cvt_pk_fp8_f32 v36, v43, v39
	v_cvt_pk_fp8_f32 v37, v49, v51
	v_cvt_pk_fp8_f32 v46, v40, v44 op_sel:[0,0,1]
	s_waitcnt lgkmcnt(0)
	v_cvt_pk_fp8_f32 v47, v64, v68 op_sel:[0,0,1]
	v_cvt_pk_fp8_f32 v36, v41, v45 op_sel:[0,0,1]
	v_cvt_pk_fp8_f32 v37, v65, v69 op_sel:[0,0,1]
	v_add_lshl_u32 v4, s2, v55, 12
	v_lshl_add_u64 v[38:39], v[66:67], 0, v[4:5]
	v_add_lshl_u32 v4, s2, v56, 12
	global_store_dwordx2 v[38:39], v[46:47], off
	v_lshl_add_u64 v[38:39], v[66:67], 0, v[4:5]
	global_store_dwordx2 v[38:39], v[36:37], off
	s_waitcnt lgkmcnt(0)
	s_branch .LBB0_23

.LBB0_582:
	v_lshl_add_u32 v188, s81, 14, v152
	ds_read_b64_tr_b16 v[172:173],v188 offset:0
	ds_read_b64_tr_b16 v[174:175],v188 offset:512
	ds_read_b64_tr_b16 v[176:177],v188 offset:1024
	ds_read_b64_tr_b16 v[178:179],v188 offset:1536
	ds_read_b64_tr_b16 v[180:181],v188 offset:2048
	ds_read_b64_tr_b16 v[182:183],v188 offset:2560
	ds_read_b64_tr_b16 v[184:185],v188 offset:3072
	v_exp_f32_e32 v66, v66
	v_exp_f32_e32 v82, v82
	v_exp_f32_e32 v67, v67
	v_exp_f32_e32 v83, v83
	v_exp_f32_e32 v68, v68
	v_exp_f32_e32 v84, v84
	v_exp_f32_e32 v69, v69
	v_exp_f32_e32 v85, v85
	v_exp_f32_e32 v70, v70
	v_exp_f32_e32 v86, v86
	v_exp_f32_e32 v71, v71
	v_exp_f32_e32 v87, v87
	v_exp_f32_e32 v72, v72
	v_exp_f32_e32 v88, v88
	v_exp_f32_e32 v73, v73
	v_exp_f32_e32 v89, v89
	v_exp_f32_e32 v74, v74
	v_exp_f32_e32 v90, v90
	v_exp_f32_e32 v75, v75
	v_exp_f32_e32 v91, v91
	v_exp_f32_e32 v76, v76
	v_exp_f32_e32 v92, v92
	v_exp_f32_e32 v77, v77
	v_exp_f32_e32 v93, v93
	v_exp_f32_e32 v78, v78
	v_exp_f32_e32 v94, v94
	v_exp_f32_e32 v79, v79
	v_exp_f32_e32 v95, v95
	v_exp_f32_e32 v80, v80
	v_exp_f32_e32 v96, v96
	v_exp_f32_e32 v81, v81
	v_exp_f32_e32 v97, v97
	ds_read_b64_tr_b16 v[186:187],v188 offset:3584
	s_waitcnt lgkmcnt(0)
	v_cvt_pk_bf16_f32 v156, v66, v67
	v_cvt_pk_bf16_f32 v157, v68, v69
	v_cvt_pk_bf16_f32 v158, v70, v71
	v_cvt_pk_bf16_f32 v159, v72, v73
	v_cvt_pk_bf16_f32 v160, v74, v75
	v_cvt_pk_bf16_f32 v161, v76, v77
	v_cvt_pk_bf16_f32 v162, v78, v79
	v_cvt_pk_bf16_f32 v163, v80, v81
	v_cvt_pk_bf16_f32 v164, v82, v83
	v_cvt_pk_bf16_f32 v165, v84, v85
	v_cvt_pk_bf16_f32 v166, v86, v87
	v_cvt_pk_bf16_f32 v167, v88, v89
	v_cvt_pk_bf16_f32 v168, v90, v91
	v_cvt_pk_bf16_f32 v169, v92, v93
	v_cvt_pk_bf16_f32 v170, v94, v95
	v_cvt_pk_bf16_f32 v171, v96, v97
	s_nop 0
	v_mfma_f32_32x32x16_bf16 v[2:17], v[156:159], v[172:175], v[2:17]
	ds_read_b64_tr_b16 v[172:173],v188 offset:4096
	ds_read_b64_tr_b16 v[174:175],v188 offset:4608
	v_mfma_f32_32x32x16_bf16 v[2:17], v[160:163], v[176:179], v[2:17]
	ds_read_b64_tr_b16 v[176:177],v188 offset:5120
	ds_read_b64_tr_b16 v[178:179],v188 offset:5632
	v_mfma_f32_32x32x16_bf16 v[2:17], v[164:167], v[180:183], v[2:17]
	ds_read_b64_tr_b16 v[180:181],v188 offset:6144
	ds_read_b64_tr_b16 v[182:183],v188 offset:6656
	v_mfma_f32_32x32x16_bf16 v[2:17], v[168:171], v[184:187], v[2:17]
	ds_read_b64_tr_b16 v[184:185],v188 offset:7168
	ds_read_b64_tr_b16 v[186:187],v188 offset:7680
	s_waitcnt lgkmcnt(0)
	v_mfma_f32_32x32x16_bf16 v[50:65], v[156:159], v[172:175], v[50:65]
	ds_read_b64_tr_b16 v[172:173],v188 offset:8192
	ds_read_b64_tr_b16 v[174:175],v188 offset:8704
	v_mfma_f32_32x32x16_bf16 v[50:65], v[160:163], v[176:179], v[50:65]
	ds_read_b64_tr_b16 v[176:177],v188 offset:9216
	ds_read_b64_tr_b16 v[178:179],v188 offset:9728
	v_mfma_f32_32x32x16_bf16 v[50:65], v[164:167], v[180:183], v[50:65]
	ds_read_b64_tr_b16 v[180:181],v188 offset:10240
	ds_read_b64_tr_b16 v[182:183],v188 offset:10752
	v_mfma_f32_32x32x16_bf16 v[50:65], v[168:171], v[184:187], v[50:65]
	ds_read_b64_tr_b16 v[184:185],v188 offset:11264
	ds_read_b64_tr_b16 v[186:187],v188 offset:11776
	s_waitcnt lgkmcnt(0)
	v_mfma_f32_32x32x16_bf16 v[34:49], v[156:159], v[172:175], v[34:49]
	ds_read_b64_tr_b16 v[172:173],v188 offset:12288
	ds_read_b64_tr_b16 v[174:175],v188 offset:12800
	v_mfma_f32_32x32x16_bf16 v[34:49], v[160:163], v[176:179], v[34:49]
	ds_read_b64_tr_b16 v[176:177],v188 offset:13312
	ds_read_b64_tr_b16 v[178:179],v188 offset:13824
	v_mfma_f32_32x32x16_bf16 v[34:49], v[164:167], v[180:183], v[34:49]
	ds_read_b64_tr_b16 v[180:181],v188 offset:14336
	ds_read_b64_tr_b16 v[182:183],v188 offset:14848
	v_mfma_f32_32x32x16_bf16 v[34:49], v[168:171], v[184:187], v[34:49]
	ds_read_b64_tr_b16 v[184:185],v188 offset:15360
	ds_read_b64_tr_b16 v[186:187],v188 offset:15872
	s_waitcnt lgkmcnt(0)
	v_mfma_f32_32x32x16_bf16 v[18:33], v[156:159], v[172:175], v[18:33]
	s_cmp_lt_u32 s83, 3
	s_cselect_b64 s[8:9], -1, 0
	s_or_b64 s[0:1], s[8:9], s[0:1]
	s_and_b64 vcc, exec, s[0:1]
	v_mfma_f32_32x32x16_bf16 v[18:33], v[160:163], v[176:179], v[18:33]
	v_mfma_f32_32x32x16_bf16 v[18:33], v[164:167], v[180:183], v[18:33]
	v_mfma_f32_32x32x16_bf16 v[18:33], v[168:171], v[184:187], v[18:33]
	s_cbranch_vccnz .LBB0_586
	v_cvt_f32_i32_e32 v156, v153
	v_fma_f32 v156, v117, v156, v150
	v_sub_f32_e32 v156, v156, v155
	s_nop 1
	v_max_f32_dpp v156, v156, v156 row_ror:1 row_mask:0xf bank_mask:0xf
	s_nop 1
	v_max_f32_dpp v156, v156, v156 row_ror:2 row_mask:0xf bank_mask:0xf
	s_nop 1
	v_max_f32_dpp v156, v156, v156 row_ror:4 row_mask:0xf bank_mask:0xf
	s_nop 1
	v_max_f32_dpp v156, v156, v156 row_ror:8 row_mask:0xf bank_mask:0xf
	s_nop 1
	v_readlane_b32 s9, v156, 16
	s_and_saveexec_b64 s[0:1], s[6:7]
	s_cbranch_execz .LBB0_585
	s_and_b32 s8, s80, 8
	s_lshl_b32 s8, s8, 2
	s_add_i32 s8, s68, s8
	v_max_f32_e32 v156, s9, v156
	v_mov_b32_e32 v157, s8
	ds_write_b32 v157, v156
